# GEMM2 epilogue hand-written: four groups of x in flight in dead K-loop operand registers, quad-per-line x loads with ds_bpermute back to the accumulator layout
# speedup vs baseline: 1.0057x; 1.0057x over previous
.LBB0_1298:
	v_lshl_add_u32 v152, s58, 8, v155
	v_lshl_or_b32 v150, s59, 8, v157
	s_and_b64 vcc, exec, s[36:37]
	s_mov_b64 s[36:37], -1
	v_lshlrev_b32_e32 v221, 2, v150
	v_lshl_add_u32 v220, v152, 12, v221
	v_lshrrev_b32_e32 v221, 1, v220
	v_mbcnt_lo_u32_b32 v222, -1, 0
	v_mbcnt_hi_u32_b32 v222, -1, v222
	v_and_b32_e32 v223, 15, v222
	v_lshrrev_b32_e32 v224, 2, v222
	v_sub_u32_e32 v224, v224, v223
	v_lshrrev_b32_e32 v223, 4, v222
	v_and_b32_e32 v225, 3, v222
	v_sub_u32_e32 v225, v225, v223
	v_lshlrev_b32_e32 v224, 12, v224
	v_lshl_add_u32 v224, v225, 5, v224
	v_add_u32_e32 v223, v220, v224
	v_and_b32_e32 v224, 15, v222
	v_lshrrev_b32_e32 v225, 4, v222
	v_lshl_or_b32 v224, v224, 2, v225
	v_lshlrev_b32_e32 v224, 2, v224
	s_mov_b64 s[62:63], s[4:5]
	global_load_dwordx4 v[144:147], v223, s[62:63] nt
	global_load_dwordx4 v[148:151], v223, s[62:63] offset:16 nt
	s_add_u32 s62, s4, 0x10000
	s_addc_u32 s63, s5, 0
	global_load_dwordx4 v[164:167], v223, s[62:63] nt
	global_load_dwordx4 v[168:171], v223, s[62:63] offset:16 nt
	s_add_u32 s62, s4, 0x20000
	s_addc_u32 s63, s5, 0
	global_load_dwordx4 v[172:175], v223, s[62:63] nt
	global_load_dwordx4 v[176:179], v223, s[62:63] offset:16 nt
	s_add_u32 s62, s4, 0x30000
	s_addc_u32 s63, s5, 0
	global_load_dwordx4 v[180:183], v223, s[62:63] nt
	global_load_dwordx4 v[184:187], v223, s[62:63] offset:16 nt
	s_waitcnt vmcnt(6)
	ds_bpermute_b32 v188, v224, v144
	ds_bpermute_b32 v189, v224, v145
	ds_bpermute_b32 v190, v224, v146
	ds_bpermute_b32 v191, v224, v147
	ds_bpermute_b32 v192, v224, v148
	ds_bpermute_b32 v193, v224, v149
	ds_bpermute_b32 v194, v224, v150
	ds_bpermute_b32 v195, v224, v151
	s_add_u32 s62, s4, 0x80000
	s_addc_u32 s63, s5, 0
	global_load_dwordx4 v[144:147], v223, s[62:63] nt
	global_load_dwordx4 v[148:151], v223, s[62:63] offset:16 nt
	s_waitcnt lgkmcnt(0)
	v_pk_add_f32 v[124:125], v[124:125], v[188:189]
	v_pk_add_f32 v[126:127], v[126:127], v[190:191]
	v_pk_add_f32 v[120:121], v[120:121], v[192:193]
	v_pk_add_f32 v[122:123], v[122:123], v[194:195]
	v_cvt_pk_bf16_f32 v124, v124, v125
	v_cvt_pk_bf16_f32 v125, v126, v127
	v_cvt_pk_bf16_f32 v126, v120, v121
	v_cvt_pk_bf16_f32 v127, v122, v123
	s_mov_b64 s[64:65], s[86:87]
	global_store_dwordx4 v221, v[124:127], s[64:65]
	s_waitcnt vmcnt(7)
	ds_bpermute_b32 v196, v224, v164
	ds_bpermute_b32 v197, v224, v165
	ds_bpermute_b32 v198, v224, v166
	ds_bpermute_b32 v199, v224, v167
	ds_bpermute_b32 v200, v224, v168
	ds_bpermute_b32 v201, v224, v169
	ds_bpermute_b32 v202, v224, v170
	ds_bpermute_b32 v203, v224, v171
	s_add_u32 s62, s4, 0x90000
	s_addc_u32 s63, s5, 0
	global_load_dwordx4 v[164:167], v223, s[62:63] nt
	global_load_dwordx4 v[168:171], v223, s[62:63] offset:16 nt
	s_waitcnt lgkmcnt(0)
	v_pk_add_f32 v[116:117], v[116:117], v[196:197]
	v_pk_add_f32 v[118:119], v[118:119], v[198:199]
	v_pk_add_f32 v[112:113], v[112:113], v[200:201]
	v_pk_add_f32 v[114:115], v[114:115], v[202:203]
	v_cvt_pk_bf16_f32 v116, v116, v117
	v_cvt_pk_bf16_f32 v117, v118, v119
	v_cvt_pk_bf16_f32 v118, v112, v113
	v_cvt_pk_bf16_f32 v119, v114, v115
	s_add_u32 s64, s86, 0x8000
	s_addc_u32 s65, s87, 0
	global_store_dwordx4 v221, v[116:119], s[64:65]
	s_waitcnt vmcnt(8)
	ds_bpermute_b32 v204, v224, v172
	ds_bpermute_b32 v205, v224, v173
	ds_bpermute_b32 v206, v224, v174
	ds_bpermute_b32 v207, v224, v175
	ds_bpermute_b32 v208, v224, v176
	ds_bpermute_b32 v209, v224, v177
	ds_bpermute_b32 v210, v224, v178
	ds_bpermute_b32 v211, v224, v179
	s_add_u32 s62, s4, 0xa0000
	s_addc_u32 s63, s5, 0
	global_load_dwordx4 v[172:175], v223, s[62:63] nt
	global_load_dwordx4 v[176:179], v223, s[62:63] offset:16 nt
	s_waitcnt lgkmcnt(0)
	v_pk_add_f32 v[108:109], v[108:109], v[204:205]
	v_pk_add_f32 v[110:111], v[110:111], v[206:207]
	v_pk_add_f32 v[104:105], v[104:105], v[208:209]
	v_pk_add_f32 v[106:107], v[106:107], v[210:211]
	v_cvt_pk_bf16_f32 v108, v108, v109
	v_cvt_pk_bf16_f32 v109, v110, v111
	v_cvt_pk_bf16_f32 v110, v104, v105
	v_cvt_pk_bf16_f32 v111, v106, v107
	s_add_u32 s64, s86, 0x10000
	s_addc_u32 s65, s87, 0
	global_store_dwordx4 v221, v[108:111], s[64:65]
	s_waitcnt vmcnt(9)
	ds_bpermute_b32 v212, v224, v180
	ds_bpermute_b32 v213, v224, v181
	ds_bpermute_b32 v214, v224, v182
	ds_bpermute_b32 v215, v224, v183
	ds_bpermute_b32 v216, v224, v184
	ds_bpermute_b32 v217, v224, v185
	ds_bpermute_b32 v218, v224, v186
	ds_bpermute_b32 v219, v224, v187
	s_add_u32 s62, s4, 0xb0000
	s_addc_u32 s63, s5, 0
	global_load_dwordx4 v[180:183], v223, s[62:63] nt
	global_load_dwordx4 v[184:187], v223, s[62:63] offset:16 nt
	s_waitcnt lgkmcnt(0)
	v_pk_add_f32 v[100:101], v[100:101], v[212:213]
	v_pk_add_f32 v[102:103], v[102:103], v[214:215]
	v_pk_add_f32 v[96:97], v[96:97], v[216:217]
	v_pk_add_f32 v[98:99], v[98:99], v[218:219]
	v_cvt_pk_bf16_f32 v100, v100, v101
	v_cvt_pk_bf16_f32 v101, v102, v103
	v_cvt_pk_bf16_f32 v102, v96, v97
	v_cvt_pk_bf16_f32 v103, v98, v99
	s_add_u32 s64, s86, 0x18000
	s_addc_u32 s65, s87, 0
	global_store_dwordx4 v221, v[100:103], s[64:65]
	s_waitcnt vmcnt(10)
	ds_bpermute_b32 v188, v224, v144
	ds_bpermute_b32 v189, v224, v145
	ds_bpermute_b32 v190, v224, v146
	ds_bpermute_b32 v191, v224, v147
	ds_bpermute_b32 v192, v224, v148
	ds_bpermute_b32 v193, v224, v149
	ds_bpermute_b32 v194, v224, v150
	ds_bpermute_b32 v195, v224, v151
	s_add_u32 s62, s4, 0x200
	s_addc_u32 s63, s5, 0
	global_load_dwordx4 v[144:147], v223, s[62:63] nt
	global_load_dwordx4 v[148:151], v223, s[62:63] offset:16 nt
	s_waitcnt lgkmcnt(0)
	v_pk_add_f32 v[92:93], v[92:93], v[188:189]
	v_pk_add_f32 v[94:95], v[94:95], v[190:191]
	v_pk_add_f32 v[88:89], v[88:89], v[192:193]
	v_pk_add_f32 v[90:91], v[90:91], v[194:195]
	v_cvt_pk_bf16_f32 v92, v92, v93
	v_cvt_pk_bf16_f32 v93, v94, v95
	v_cvt_pk_bf16_f32 v94, v88, v89
	v_cvt_pk_bf16_f32 v95, v90, v91
	s_add_u32 s64, s86, 0x40000
	s_addc_u32 s65, s87, 0
	global_store_dwordx4 v221, v[92:95], s[64:65]
	s_waitcnt vmcnt(10)
	ds_bpermute_b32 v196, v224, v164
	ds_bpermute_b32 v197, v224, v165
	ds_bpermute_b32 v198, v224, v166
	ds_bpermute_b32 v199, v224, v167
	ds_bpermute_b32 v200, v224, v168
	ds_bpermute_b32 v201, v224, v169
	ds_bpermute_b32 v202, v224, v170
	ds_bpermute_b32 v203, v224, v171
	s_add_u32 s62, s4, 0x10200
	s_addc_u32 s63, s5, 0
	global_load_dwordx4 v[164:167], v223, s[62:63] nt
	global_load_dwordx4 v[168:171], v223, s[62:63] offset:16 nt
	s_waitcnt lgkmcnt(0)
	v_pk_add_f32 v[84:85], v[84:85], v[196:197]
	v_pk_add_f32 v[86:87], v[86:87], v[198:199]
	v_pk_add_f32 v[80:81], v[80:81], v[200:201]
	v_pk_add_f32 v[82:83], v[82:83], v[202:203]
	v_cvt_pk_bf16_f32 v84, v84, v85
	v_cvt_pk_bf16_f32 v85, v86, v87
	v_cvt_pk_bf16_f32 v86, v80, v81
	v_cvt_pk_bf16_f32 v87, v82, v83
	s_add_u32 s64, s86, 0x48000
	s_addc_u32 s65, s87, 0
	global_store_dwordx4 v221, v[84:87], s[64:65]
	s_waitcnt vmcnt(10)
	ds_bpermute_b32 v204, v224, v172
	ds_bpermute_b32 v205, v224, v173
	ds_bpermute_b32 v206, v224, v174
	ds_bpermute_b32 v207, v224, v175
	ds_bpermute_b32 v208, v224, v176
	ds_bpermute_b32 v209, v224, v177
	ds_bpermute_b32 v210, v224, v178
	ds_bpermute_b32 v211, v224, v179
	s_add_u32 s62, s4, 0x20200
	s_addc_u32 s63, s5, 0
	global_load_dwordx4 v[172:175], v223, s[62:63] nt
	global_load_dwordx4 v[176:179], v223, s[62:63] offset:16 nt
	s_waitcnt lgkmcnt(0)
	v_pk_add_f32 v[76:77], v[76:77], v[204:205]
	v_pk_add_f32 v[78:79], v[78:79], v[206:207]
	v_pk_add_f32 v[68:69], v[68:69], v[208:209]
	v_pk_add_f32 v[70:71], v[70:71], v[210:211]
	v_cvt_pk_bf16_f32 v76, v76, v77
	v_cvt_pk_bf16_f32 v77, v78, v79
	v_cvt_pk_bf16_f32 v78, v68, v69
	v_cvt_pk_bf16_f32 v79, v70, v71
	s_add_u32 s64, s86, 0x50000
	s_addc_u32 s65, s87, 0
	global_store_dwordx4 v221, v[76:79], s[64:65]
	s_waitcnt vmcnt(10)
	ds_bpermute_b32 v212, v224, v180
	ds_bpermute_b32 v213, v224, v181
	ds_bpermute_b32 v214, v224, v182
	ds_bpermute_b32 v215, v224, v183
	ds_bpermute_b32 v216, v224, v184
	ds_bpermute_b32 v217, v224, v185
	ds_bpermute_b32 v218, v224, v186
	ds_bpermute_b32 v219, v224, v187
	s_add_u32 s62, s4, 0x30200
	s_addc_u32 s63, s5, 0
	global_load_dwordx4 v[180:183], v223, s[62:63] nt
	global_load_dwordx4 v[184:187], v223, s[62:63] offset:16 nt
	s_waitcnt lgkmcnt(0)
	v_pk_add_f32 v[56:57], v[56:57], v[212:213]
	v_pk_add_f32 v[58:59], v[58:59], v[214:215]
	v_pk_add_f32 v[48:49], v[48:49], v[216:217]
	v_pk_add_f32 v[50:51], v[50:51], v[218:219]
	v_cvt_pk_bf16_f32 v56, v56, v57
	v_cvt_pk_bf16_f32 v57, v58, v59
	v_cvt_pk_bf16_f32 v58, v48, v49
	v_cvt_pk_bf16_f32 v59, v50, v51
	s_add_u32 s64, s86, 0x58000
	s_addc_u32 s65, s87, 0
	global_store_dwordx4 v221, v[56:59], s[64:65]
	s_waitcnt vmcnt(10)
	ds_bpermute_b32 v188, v224, v144
	ds_bpermute_b32 v189, v224, v145
	ds_bpermute_b32 v190, v224, v146
	ds_bpermute_b32 v191, v224, v147
	ds_bpermute_b32 v192, v224, v148
	ds_bpermute_b32 v193, v224, v149
	ds_bpermute_b32 v194, v224, v150
	ds_bpermute_b32 v195, v224, v151
	s_add_u32 s62, s4, 0x80200
	s_addc_u32 s63, s5, 0
	global_load_dwordx4 v[144:147], v223, s[62:63] nt
	global_load_dwordx4 v[148:151], v223, s[62:63] offset:16 nt
	s_waitcnt lgkmcnt(0)
	v_pk_add_f32 v[72:73], v[72:73], v[188:189]
	v_pk_add_f32 v[74:75], v[74:75], v[190:191]
	v_pk_add_f32 v[64:65], v[64:65], v[192:193]
	v_pk_add_f32 v[66:67], v[66:67], v[194:195]
	v_cvt_pk_bf16_f32 v72, v72, v73
	v_cvt_pk_bf16_f32 v73, v74, v75
	v_cvt_pk_bf16_f32 v74, v64, v65
	v_cvt_pk_bf16_f32 v75, v66, v67
	s_add_u32 s64, s86, 0x100
	s_addc_u32 s65, s87, 0
	global_store_dwordx4 v221, v[72:75], s[64:65]
	s_waitcnt vmcnt(10)
	ds_bpermute_b32 v196, v224, v164
	ds_bpermute_b32 v197, v224, v165
	ds_bpermute_b32 v198, v224, v166
	ds_bpermute_b32 v199, v224, v167
	ds_bpermute_b32 v200, v224, v168
	ds_bpermute_b32 v201, v224, v169
	ds_bpermute_b32 v202, v224, v170
	ds_bpermute_b32 v203, v224, v171
	s_add_u32 s62, s4, 0x90200
	s_addc_u32 s63, s5, 0
	global_load_dwordx4 v[164:167], v223, s[62:63] nt
	global_load_dwordx4 v[168:171], v223, s[62:63] offset:16 nt
	s_waitcnt lgkmcnt(0)
	v_pk_add_f32 v[60:61], v[60:61], v[196:197]
	v_pk_add_f32 v[62:63], v[62:63], v[198:199]
	v_pk_add_f32 v[52:53], v[52:53], v[200:201]
	v_pk_add_f32 v[54:55], v[54:55], v[202:203]
	v_cvt_pk_bf16_f32 v60, v60, v61
	v_cvt_pk_bf16_f32 v61, v62, v63
	v_cvt_pk_bf16_f32 v62, v52, v53
	v_cvt_pk_bf16_f32 v63, v54, v55
	s_add_u32 s64, s86, 0x8100
	s_addc_u32 s65, s87, 0
	global_store_dwordx4 v221, v[60:63], s[64:65]
	s_waitcnt vmcnt(10)
	ds_bpermute_b32 v204, v224, v172
	ds_bpermute_b32 v205, v224, v173
	ds_bpermute_b32 v206, v224, v174
	ds_bpermute_b32 v207, v224, v175
	ds_bpermute_b32 v208, v224, v176
	ds_bpermute_b32 v209, v224, v177
	ds_bpermute_b32 v210, v224, v178
	ds_bpermute_b32 v211, v224, v179
	s_add_u32 s62, s4, 0xa0200
	s_addc_u32 s63, s5, 0
	global_load_dwordx4 v[172:175], v223, s[62:63] nt
	global_load_dwordx4 v[176:179], v223, s[62:63] offset:16 nt
	s_waitcnt lgkmcnt(0)
	v_pk_add_f32 v[44:45], v[44:45], v[204:205]
	v_pk_add_f32 v[46:47], v[46:47], v[206:207]
	v_pk_add_f32 v[40:41], v[40:41], v[208:209]
	v_pk_add_f32 v[42:43], v[42:43], v[210:211]
	v_cvt_pk_bf16_f32 v44, v44, v45
	v_cvt_pk_bf16_f32 v45, v46, v47
	v_cvt_pk_bf16_f32 v46, v40, v41
	v_cvt_pk_bf16_f32 v47, v42, v43
	s_add_u32 s64, s86, 0x10100
	s_addc_u32 s65, s87, 0
	global_store_dwordx4 v221, v[44:47], s[64:65]
	s_waitcnt vmcnt(10)
	ds_bpermute_b32 v212, v224, v180
	ds_bpermute_b32 v213, v224, v181
	ds_bpermute_b32 v214, v224, v182
	ds_bpermute_b32 v215, v224, v183
	ds_bpermute_b32 v216, v224, v184
	ds_bpermute_b32 v217, v224, v185
	ds_bpermute_b32 v218, v224, v186
	ds_bpermute_b32 v219, v224, v187
	s_add_u32 s62, s4, 0xb0200
	s_addc_u32 s63, s5, 0
	global_load_dwordx4 v[180:183], v223, s[62:63] nt
	global_load_dwordx4 v[184:187], v223, s[62:63] offset:16 nt
	s_waitcnt lgkmcnt(0)
	v_pk_add_f32 v[36:37], v[36:37], v[212:213]
	v_pk_add_f32 v[38:39], v[38:39], v[214:215]
	v_pk_add_f32 v[32:33], v[32:33], v[216:217]
	v_pk_add_f32 v[34:35], v[34:35], v[218:219]
	v_cvt_pk_bf16_f32 v36, v36, v37
	v_cvt_pk_bf16_f32 v37, v38, v39
	v_cvt_pk_bf16_f32 v38, v32, v33
	v_cvt_pk_bf16_f32 v39, v34, v35
	s_add_u32 s64, s86, 0x18100
	s_addc_u32 s65, s87, 0
	global_store_dwordx4 v221, v[36:39], s[64:65]
	s_waitcnt vmcnt(10)
	ds_bpermute_b32 v188, v224, v144
	ds_bpermute_b32 v189, v224, v145
	ds_bpermute_b32 v190, v224, v146
	ds_bpermute_b32 v191, v224, v147
	ds_bpermute_b32 v192, v224, v148
	ds_bpermute_b32 v193, v224, v149
	ds_bpermute_b32 v194, v224, v150
	ds_bpermute_b32 v195, v224, v151
	s_waitcnt lgkmcnt(0)
	v_pk_add_f32 v[28:29], v[28:29], v[188:189]
	v_pk_add_f32 v[30:31], v[30:31], v[190:191]
	v_pk_add_f32 v[24:25], v[24:25], v[192:193]
	v_pk_add_f32 v[26:27], v[26:27], v[194:195]
	v_cvt_pk_bf16_f32 v28, v28, v29
	v_cvt_pk_bf16_f32 v29, v30, v31
	v_cvt_pk_bf16_f32 v30, v24, v25
	v_cvt_pk_bf16_f32 v31, v26, v27
	s_add_u32 s64, s86, 0x40100
	s_addc_u32 s65, s87, 0
	global_store_dwordx4 v221, v[28:31], s[64:65]
	s_waitcnt vmcnt(8)
	ds_bpermute_b32 v196, v224, v164
	ds_bpermute_b32 v197, v224, v165
	ds_bpermute_b32 v198, v224, v166
	ds_bpermute_b32 v199, v224, v167
	ds_bpermute_b32 v200, v224, v168
	ds_bpermute_b32 v201, v224, v169
	ds_bpermute_b32 v202, v224, v170
	ds_bpermute_b32 v203, v224, v171
	s_waitcnt lgkmcnt(0)
	v_pk_add_f32 v[20:21], v[20:21], v[196:197]
	v_pk_add_f32 v[22:23], v[22:23], v[198:199]
	v_pk_add_f32 v[16:17], v[16:17], v[200:201]
	v_pk_add_f32 v[18:19], v[18:19], v[202:203]
	v_cvt_pk_bf16_f32 v20, v20, v21
	v_cvt_pk_bf16_f32 v21, v22, v23
	v_cvt_pk_bf16_f32 v22, v16, v17
	v_cvt_pk_bf16_f32 v23, v18, v19
	s_add_u32 s64, s86, 0x48100
	s_addc_u32 s65, s87, 0
	global_store_dwordx4 v221, v[20:23], s[64:65]
	s_waitcnt vmcnt(6)
	ds_bpermute_b32 v204, v224, v172
	ds_bpermute_b32 v205, v224, v173
	ds_bpermute_b32 v206, v224, v174
	ds_bpermute_b32 v207, v224, v175
	ds_bpermute_b32 v208, v224, v176
	ds_bpermute_b32 v209, v224, v177
	ds_bpermute_b32 v210, v224, v178
	ds_bpermute_b32 v211, v224, v179
	s_waitcnt lgkmcnt(0)
	v_pk_add_f32 v[12:13], v[12:13], v[204:205]
	v_pk_add_f32 v[14:15], v[14:15], v[206:207]
	v_pk_add_f32 v[8:9], v[8:9], v[208:209]
	v_pk_add_f32 v[10:11], v[10:11], v[210:211]
	v_cvt_pk_bf16_f32 v12, v12, v13
	v_cvt_pk_bf16_f32 v13, v14, v15
	v_cvt_pk_bf16_f32 v14, v8, v9
	v_cvt_pk_bf16_f32 v15, v10, v11
	s_add_u32 s64, s86, 0x50100
	s_addc_u32 s65, s87, 0
	global_store_dwordx4 v221, v[12:15], s[64:65]
	s_waitcnt vmcnt(4)
	ds_bpermute_b32 v212, v224, v180
	ds_bpermute_b32 v213, v224, v181
	ds_bpermute_b32 v214, v224, v182
	ds_bpermute_b32 v215, v224, v183
	ds_bpermute_b32 v216, v224, v184
	ds_bpermute_b32 v217, v224, v185
	ds_bpermute_b32 v218, v224, v186
	ds_bpermute_b32 v219, v224, v187
	s_waitcnt lgkmcnt(0)
	v_pk_add_f32 v[4:5], v[4:5], v[212:213]
	v_pk_add_f32 v[6:7], v[6:7], v[214:215]
	v_pk_add_f32 v[0:1], v[0:1], v[216:217]
	v_pk_add_f32 v[2:3], v[2:3], v[218:219]
	v_cvt_pk_bf16_f32 v4, v4, v5
	v_cvt_pk_bf16_f32 v5, v6, v7
	v_cvt_pk_bf16_f32 v6, v0, v1
	v_cvt_pk_bf16_f32 v7, v2, v3
	s_add_u32 s64, s86, 0x58100
	s_addc_u32 s65, s87, 0
	global_store_dwordx4 v221, v[4:7], s[64:65]
	s_cbranch_vccnz .LBB0_1285
	s_andn2_b64 vcc, exec, s[12:13]
	s_cbranch_vccnz .LBB0_1284
	s_barrier
	s_branch .LBB0_1284
